# v45 + GU GEMM K-loop LDS-DMA staging rebalanced 6/2 -> 4/4 per super-phase (with the no-setprio loops)
# speedup vs baseline: 1.0090x; 1.0083x over previous
; #define PG8_STAGE(bufoff, gbase, voff) do { _Pragma("unroll") for (int _i = 0; _i < 2; ++_i) \
;         __builtin_amdgcn_global_load_lds((const unsigned*)((const char*)(gbase) + (voff)[_i]), (PG8_LAS unsigned*)(lds + (bufoff) + ldsw + _i * 8192), 16, 0, 0); } while (0)
; #define PG8_WAIT_V(n) asm volatile("s_waitcnt vmcnt(" #n ")" ::: "memory")
; #define PG8_BAR __builtin_amdgcn_s_barrier()
; template <class Epi, class Sched, bool ALIGN_EPI = false, bool SP2 = false>
; __device__ __forceinline__ void gemm_phase(PG8_LAS unsigned char* lds, const Gemm g, const Sched& S, const Epi& E) {
;     ...
;     for (int i = 0; i < 2; ++i) { int R, C; stage_rc(tid * 16 + i * 8192, R, C); const int Rb = Epi::PERM ? ((R & ~31) + perm32(R & 31)) : R;
;         voffA[i] = (unsigned)(R * K + C) * 2u; voffB[i] = (unsigned)(Rb * K + C) * 2u; }
;     const size_t kstep = (size_t)(BK * 2);
;     const size_t hstep = (size_t)HALF * K * 2;
;     const size_t tstep = 2 * hstep;
;     const unsigned ldsw = (unsigned)wid * 1024u;
;     const int aoff = lds_byte(wr * 64 + fr, fq * 8), boff = lds_byte(wc * 32 + fr, fq * 8);
;     ...
;         PG8_STAGE(PG8_SB(0, 0), cB, voffB); PG8_STAGE(PG8_SB(0, 1), cB + hstep, voffB); PG8_STAGE(PG8_SA(0, 0), cA, voffA); PG8_STAGE(PG8_SA(0, 1), cA + hstep, voffA);
;         if (wr == 1) PG8_BAR;
;         PG8_WAIT_V(2); PG8_BAR;
;         PG8_STAGE(PG8_SB(1, 0), cB + kstep, voffB); PG8_STAGE(PG8_SA(1, 0), cA + kstep, voffA); PG8_STAGE(PG8_SB(1, 1), cB + hstep + kstep, voffB);
;         PG8_WAIT_V(6); PG8_BAR;
.LBB0_393:
	v_readlane_b32 s38, v254, 9
	s_lshl_b32 s7, s7, 5
	v_mov_b32_e32 v133, v157
	v_readlane_b32 s39, v254, 10
	s_and_b32 s14, s7, 0x60
	s_add_i32 m0, s25, 0x18000
	v_lshl_add_u64 v[0:1], v[0:1], 0, s[96:97]
	v_lshl_add_u64 v[12:13], s[38:39], 0, v[132:133]
	v_mov_b32_e32 v131, v157
	s_lshl_b32 s9, s8, 13
	s_lshl_b32 s7, s14, 7
	s_waitcnt vmcnt(2)
	s_barrier
	global_load_lds_dwordx4 v[0:1], off
	v_lshl_add_u64 v[0:1], v[2:3], 0, s[96:97]
	s_add_i32 m0, s25, 0x1a000
	s_add_i32 s29, s25, 0x8000
	s_add_i32 s30, s25, 0xa000
	v_lshl_add_u64 v[14:15], s[38:39], 0, v[130:131]
	global_load_lds_dwordx4 v[0:1], off
	s_add_u32 s10, s12, 0x40080
	s_addc_u32 s11, s13, 0
	s_add_i32 m0, s25, 0x1c000
	v_lshl_add_u64 v[0:1], s[10:11], 0, v[156:157]
	global_load_lds_dwordx4 v[0:1], off
	v_lshl_add_u64 v[0:1], s[10:11], 0, v[128:129]
	s_add_i32 m0, s25, 0x1e000
	s_cmpk_lt_u32 s6, 0x100
	global_load_lds_dwordx4 v[0:1], off
	v_lshrrev_b32_e32 v1, 1, v4
	v_and_b32_e32 v1, 24, v1
	v_and_b32_e32 v0, 15, v4
	v_lshlrev_b32_e32 v2, 1, v1
	v_lshl_or_b32 v148, s8, 6, v0
	v_lshl_or_b32 v2, v0, 6, v2
	v_lshlrev_b32_e32 v0, 2, v0
	v_and_b32_e32 v3, 32, v0
	v_bitop3_b32 v149, v2, s7, v3 bitop3:0xde
	s_cselect_b64 s[6:7], -1, 0
	s_lshl_b32 s8, s8, 8
	s_add_i32 s8, s8, 0
	s_add_i32 s8, s8, 0x20000
	v_add_u32_e32 v150, s8, v0
	v_lshlrev_b32_e32 v0, 14, v9
	v_and_b32_e32 v0, 0xffff8000, v0
	v_or_b32_e32 v151, s14, v1
	v_lshl_add_u32 v0, v8, 11, v0
	v_and_b32_e32 v1, 1, v9
	v_lshl_or_b32 v0, v1, 6, v0
	v_lshl_add_u32 v134, v10, 1, v0
	v_lshlrev_b32_e32 v0, 14, v5
	v_and_b32_e32 v0, 0xffff8000, v0
	s_waitcnt vmcnt(4)
	v_lshl_add_u32 v0, v6, 11, v0
	v_and_b32_e32 v1, 1, v5
	v_bitop3_b32 v4, v2, s9, v3 bitop3:0xde
	v_lshl_or_b32 v0, v1, 6, v0
	v_readlane_b32 s8, v254, 7
	v_mov_b32_e32 v135, v157
	v_lshl_add_u32 v136, v7, 1, v0
	v_mov_b32_e32 v137, v157
	s_mov_b32 s31, 0
	v_add_u32_e32 v152, 0, v4
	v_readlane_b32 s34, v254, 3
	s_mov_b32 s35, s8
	s_mov_b64 s[10:11], s[38:39]
	s_barrier
	v_readlane_b32 s9, v254, 8
	s_branch .LBB0_396

; #define PG8_STAGE(bufoff, gbase, voff) do { _Pragma("unroll") for (int _i = 0; _i < 2; ++_i) \
;         __builtin_amdgcn_global_load_lds((const unsigned*)((const char*)(gbase) + (voff)[_i]), (PG8_LAS unsigned*)(lds + (bufoff) + ldsw + _i * 8192), 16, 0, 0); } while (0)
; #define PG8_LDA(dst, b, h) do { _Pragma("unroll") for (int m = 0; m < 4; ++m) _Pragma("unroll") for (int k = 0; k < 2; ++k) dst[m][k] = *(const PG8_LAS bf16x8*)(lds + PG8_SA(b, h) + aoff + m * 2048 + k * 1024); } while (0)
; #define PG8_LDB(dst, b, h) do { _Pragma("unroll") for (int n = 0; n < 2; ++n) _Pragma("unroll") for (int k = 0; k < 2; ++k) dst[n][k] = *(const PG8_LAS bf16x8*)(lds + PG8_SB(b, h) + boff + n * 2048 + k * 1024); } while (0)
; #define PG8_MMA(ai, bj, At, Bt) do { __builtin_amdgcn_s_setprio(1); _Pragma("unroll") for (int m = 0; m < 4; ++m) _Pragma("unroll") for (int n = 0; n < 2; ++n) _Pragma("unroll") for (int k = 0; k < 2; ++k) \
;         acc[ai][bj][m][n] = __builtin_amdgcn_mfma_f32_16x16x32_bf16(Bt[n][k], At[m][k], acc[ai][bj][m][n], 0, 0, 0); __builtin_amdgcn_s_setprio(0); } while (0)
; #define PG8_WAIT_V(n) asm volatile("s_waitcnt vmcnt(" #n ")" ::: "memory")
; #define PG8_WAIT_L(n) asm volatile("s_waitcnt lgkmcnt(" #n ")" ::: "memory")
; #define PG8_BAR __builtin_amdgcn_s_barrier()
; #define PG8_SCHED __builtin_amdgcn_sched_barrier(0)
; template <class Epi, class Sched, bool ALIGN_EPI = false, bool SP2 = false>
; __device__ __forceinline__ void gemm_phase(PG8_LAS unsigned char* lds, const Gemm g, const Sched& S, const Epi& E) {
;     ...
;             PG8_LDB(B0, 0, 0); PG8_LDB(B1, 0, 1); PG8_SCHED; PG8_LDA(At, 0, 0); PG8_STAGE(PG8_SA(1, 1), a1 + hstep, voffA);
;             PG8_WAIT_V(8); PG8_WAIT_L(0); PG8_BAR; PG8_MMA(0, 0, At, B0); PG8_MMA(0, 1, At, B1); PG8_BAR; PG8_SCHED;
;             PG8_LDA(At, 0, 1); PG8_STAGE(PG8_SB(0, 0), b2, voffB); PG8_STAGE(PG8_SB(0, 1), b2 + hstep, voffB); PG8_STAGE(PG8_SA(0, 0), a2, voffA);
.LBB0_399:
	s_add_u32 s12, s10, 0xfffc0080
	s_addc_u32 s13, s11, -1
	s_add_i32 s51, 0, 0x10000
	s_cmp_eq_u32 s50, 12
	s_cselect_b32 s15, s41, s13
	s_cselect_b32 s14, s46, s12
	v_add_u32_e32 v146, s51, v149
	s_cselect_b32 s13, s9, s49
	s_cselect_b32 s12, s47, s48
	s_add_i32 s54, 0, 0x14000
	ds_read_b128 v[138:141], v146
	ds_read_b128 v[142:145], v146 offset:1024
	ds_read_b128 v[168:171], v146 offset:2048
	ds_read_b128 v[172:175], v146 offset:3072
	v_add_u32_e32 v146, s54, v149
	ds_read_b128 v[176:179], v146
	ds_read_b128 v[180:183], v146 offset:1024
	ds_read_b128 v[184:187], v146 offset:2048
	ds_read_b128 v[188:191], v146 offset:3072
	s_add_u32 s52, s10, 0xfffc0000
	s_addc_u32 s53, s11, -1
	v_lshl_add_u64 v[224:225], s[52:53], 0, v[132:133]
	v_lshl_add_u64 v[226:227], s[52:53], 0, v[130:131]
	v_lshl_add_u64 v[146:147], s[10:11], 0, v[134:135]
	s_mov_b32 m0, s29
	ds_read_b128 v[192:195], v152
	ds_read_b128 v[196:199], v152 offset:1024
	ds_read_b128 v[200:203], v152 offset:2048
	ds_read_b128 v[204:207], v152 offset:3072
	ds_read_b128 v[208:211], v152 offset:4096
	ds_read_b128 v[212:215], v152 offset:5120
	ds_read_b128 v[216:219], v152 offset:6144
	ds_read_b128 v[220:223], v152 offset:7168
	global_load_lds_dwordx4 v[224:225], off
	s_mov_b32 m0, s30
	s_nop 0
	global_load_lds_dwordx4 v[226:227], off
	s_add_i32 m0, s25, 0xc000
	s_nop 0
	global_load_lds_dwordx4 v[146:147], off
	v_lshl_add_u64 v[146:147], s[10:11], 0, v[136:137]
	s_add_i32 m0, s25, 0xe000
	s_nop 0
	global_load_lds_dwordx4 v[146:147], off
	s_waitcnt vmcnt(8)
	s_waitcnt lgkmcnt(0)
	s_barrier
	s_waitcnt lgkmcnt(0)
	v_mfma_f32_16x16x32_bf16 v[124:127], v[138:141], v[192:195], v[124:127]
	v_mfma_f32_16x16x32_bf16 v[120:123], v[168:171], v[192:195], v[120:123]
	v_mfma_f32_16x16x32_bf16 v[108:111], v[138:141], v[200:203], v[108:111]
	v_mfma_f32_16x16x32_bf16 v[104:107], v[168:171], v[200:203], v[104:107]
	v_mfma_f32_16x16x32_bf16 v[92:95], v[138:141], v[208:211], v[92:95]
	v_mfma_f32_16x16x32_bf16 v[88:91], v[168:171], v[208:211], v[88:91]
	v_mfma_f32_16x16x32_bf16 v[76:79], v[138:141], v[216:219], v[76:79]
	v_mfma_f32_16x16x32_bf16 v[72:75], v[168:171], v[216:219], v[72:75]
	v_mfma_f32_16x16x32_bf16 v[124:127], v[142:145], v[196:199], v[124:127]
	v_mfma_f32_16x16x32_bf16 v[120:123], v[172:175], v[196:199], v[120:123]
	v_mfma_f32_16x16x32_bf16 v[108:111], v[142:145], v[204:207], v[108:111]
	v_mfma_f32_16x16x32_bf16 v[104:107], v[172:175], v[204:207], v[104:107]
	v_mfma_f32_16x16x32_bf16 v[92:95], v[142:145], v[212:215], v[92:95]
	v_mfma_f32_16x16x32_bf16 v[88:91], v[172:175], v[212:215], v[88:91]
	v_mfma_f32_16x16x32_bf16 v[76:79], v[142:145], v[220:223], v[76:79]
	v_mfma_f32_16x16x32_bf16 v[72:75], v[172:175], v[220:223], v[72:75]
	v_mfma_f32_16x16x32_bf16 v[116:119], v[176:179], v[192:195], v[116:119]
	v_mfma_f32_16x16x32_bf16 v[112:115], v[184:187], v[192:195], v[112:115]
	v_mfma_f32_16x16x32_bf16 v[100:103], v[176:179], v[200:203], v[100:103]
	v_mfma_f32_16x16x32_bf16 v[96:99], v[184:187], v[200:203], v[96:99]
	v_mfma_f32_16x16x32_bf16 v[84:87], v[176:179], v[208:211], v[84:87]
	v_mfma_f32_16x16x32_bf16 v[80:83], v[184:187], v[208:211], v[80:83]
	v_mfma_f32_16x16x32_bf16 v[68:71], v[176:179], v[216:219], v[68:71]
	v_mfma_f32_16x16x32_bf16 v[64:67], v[184:187], v[216:219], v[64:67]
	v_mfma_f32_16x16x32_bf16 v[116:119], v[180:183], v[196:199], v[116:119]
	v_mfma_f32_16x16x32_bf16 v[112:115], v[188:191], v[196:199], v[112:115]
	v_mfma_f32_16x16x32_bf16 v[100:103], v[180:183], v[204:207], v[100:103]
	v_mfma_f32_16x16x32_bf16 v[96:99], v[188:191], v[204:207], v[96:99]
	v_mfma_f32_16x16x32_bf16 v[84:87], v[180:183], v[212:215], v[84:87]
	v_mfma_f32_16x16x32_bf16 v[80:83], v[188:191], v[212:215], v[80:83]
	v_mfma_f32_16x16x32_bf16 v[68:71], v[180:183], v[220:223], v[68:71]
	v_mfma_f32_16x16x32_bf16 v[64:67], v[188:191], v[220:223], v[64:67]
	s_barrier
	s_add_i32 s51, s51, s21
	v_lshl_add_u64 v[146:147], s[12:13], 0, v[156:157]
	s_mov_b32 m0, s51
	ds_read_b128 v[192:195], v152 offset:16384
	ds_read_b128 v[196:199], v152 offset:17408
	ds_read_b128 v[200:203], v152 offset:18432
	ds_read_b128 v[204:207], v152 offset:19456
	ds_read_b128 v[208:211], v152 offset:20480
	ds_read_b128 v[212:215], v152 offset:21504
	ds_read_b128 v[216:219], v152 offset:22528
	ds_read_b128 v[220:223], v152 offset:23552
	global_load_lds_dwordx4 v[146:147], off
	s_add_i32 m0, s51, 0x2000
	s_add_u32 s52, s12, 0x40000
	v_lshl_add_u64 v[154:155], s[12:13], 0, v[128:129]
	s_addc_u32 s53, s13, 0
	s_add_i32 s51, s54, s21
	global_load_lds_dwordx4 v[154:155], off
	v_lshl_add_u64 v[224:225], s[52:53], 0, v[156:157]
	s_mov_b32 m0, s51
	s_nop 0
	global_load_lds_dwordx4 v[224:225], off
	v_lshl_add_u64 v[224:225], s[52:53], 0, v[128:129]
	s_add_i32 m0, s51, 0x2000
	s_nop 0
	global_load_lds_dwordx4 v[224:225], off
	s_waitcnt vmcnt(6)
	s_waitcnt lgkmcnt(0)
	s_barrier
; #define PG8_STAGE(bufoff, gbase, voff) do { _Pragma("unroll") for (int _i = 0; _i < 2; ++_i) \
;         __builtin_amdgcn_global_load_lds((const unsigned*)((const char*)(gbase) + (voff)[_i]), (PG8_LAS unsigned*)(lds + (bufoff) + ldsw + _i * 8192), 16, 0, 0); } while (0)
; #define PG8_LDA(dst, b, h) do { _Pragma("unroll") for (int m = 0; m < 4; ++m) _Pragma("unroll") for (int k = 0; k < 2; ++k) dst[m][k] = *(const PG8_LAS bf16x8*)(lds + PG8_SA(b, h) + aoff + m * 2048 + k * 1024); } while (0)
; #define PG8_LDB(dst, b, h) do { _Pragma("unroll") for (int n = 0; n < 2; ++n) _Pragma("unroll") for (int k = 0; k < 2; ++k) dst[n][k] = *(const PG8_LAS bf16x8*)(lds + PG8_SB(b, h) + boff + n * 2048 + k * 1024); } while (0)
; #define PG8_MMA(ai, bj, At, Bt) do { __builtin_amdgcn_s_setprio(1); _Pragma("unroll") for (int m = 0; m < 4; ++m) _Pragma("unroll") for (int n = 0; n < 2; ++n) _Pragma("unroll") for (int k = 0; k < 2; ++k) \
;         acc[ai][bj][m][n] = __builtin_amdgcn_mfma_f32_16x16x32_bf16(Bt[n][k], At[m][k], acc[ai][bj][m][n], 0, 0, 0); __builtin_amdgcn_s_setprio(0); } while (0)
; #define PG8_WAIT_V(n) asm volatile("s_waitcnt vmcnt(" #n ")" ::: "memory")
; #define PG8_WAIT_L(n) asm volatile("s_waitcnt lgkmcnt(" #n ")" ::: "memory")
; #define PG8_BAR __builtin_amdgcn_s_barrier()
; #define PG8_SCHED __builtin_amdgcn_sched_barrier(0)
; template <class Epi, class Sched, bool ALIGN_EPI = false, bool SP2 = false>
; __device__ __forceinline__ void gemm_phase(PG8_LAS unsigned char* lds, const Gemm g, const Sched& S, const Epi& E) {
;     ...
;             PG8_WAIT_V(8); PG8_WAIT_L(0); PG8_BAR; PG8_MMA(1, 0, At, B0); PG8_MMA(1, 1, At, B1); PG8_BAR; PG8_SCHED;
;             PG8_LDB(B0, 1, 0); PG8_LDB(B1, 1, 1); PG8_SCHED; PG8_LDA(At, 1, 0); PG8_STAGE(PG8_SA(0, 1), a2 + hstep, voffA);
	s_waitcnt lgkmcnt(0)
	v_mfma_f32_16x16x32_bf16 v[60:63], v[138:141], v[192:195], v[60:63]
	v_mfma_f32_16x16x32_bf16 v[56:59], v[168:171], v[192:195], v[56:59]
	v_mfma_f32_16x16x32_bf16 v[44:47], v[138:141], v[200:203], v[44:47]
	v_mfma_f32_16x16x32_bf16 v[40:43], v[168:171], v[200:203], v[40:43]
	v_mfma_f32_16x16x32_bf16 v[28:31], v[138:141], v[208:211], v[28:31]
	v_mfma_f32_16x16x32_bf16 v[24:27], v[168:171], v[208:211], v[24:27]
	v_mfma_f32_16x16x32_bf16 v[12:15], v[138:141], v[216:219], v[12:15]
	v_mfma_f32_16x16x32_bf16 v[8:11], v[168:171], v[216:219], v[8:11]
	v_mfma_f32_16x16x32_bf16 v[60:63], v[142:145], v[196:199], v[60:63]
	v_mfma_f32_16x16x32_bf16 v[56:59], v[172:175], v[196:199], v[56:59]
	v_mfma_f32_16x16x32_bf16 v[44:47], v[142:145], v[204:207], v[44:47]
	v_mfma_f32_16x16x32_bf16 v[40:43], v[172:175], v[204:207], v[40:43]
	v_mfma_f32_16x16x32_bf16 v[28:31], v[142:145], v[212:215], v[28:31]
	v_mfma_f32_16x16x32_bf16 v[24:27], v[172:175], v[212:215], v[24:27]
	v_mfma_f32_16x16x32_bf16 v[12:15], v[142:145], v[220:223], v[12:15]
	v_mfma_f32_16x16x32_bf16 v[8:11], v[172:175], v[220:223], v[8:11]
	v_mfma_f32_16x16x32_bf16 v[52:55], v[176:179], v[192:195], v[52:55]
	v_mfma_f32_16x16x32_bf16 v[48:51], v[184:187], v[192:195], v[48:51]
	v_mfma_f32_16x16x32_bf16 v[36:39], v[176:179], v[200:203], v[36:39]
	v_mfma_f32_16x16x32_bf16 v[32:35], v[184:187], v[200:203], v[32:35]
	v_mfma_f32_16x16x32_bf16 v[20:23], v[176:179], v[208:211], v[20:23]
	v_mfma_f32_16x16x32_bf16 v[16:19], v[184:187], v[208:211], v[16:19]
	v_mfma_f32_16x16x32_bf16 v[4:7], v[176:179], v[216:219], v[4:7]
	v_mfma_f32_16x16x32_bf16 v[0:3], v[184:187], v[216:219], v[0:3]
	v_mfma_f32_16x16x32_bf16 v[52:55], v[180:183], v[196:199], v[52:55]
	v_mfma_f32_16x16x32_bf16 v[48:51], v[188:191], v[196:199], v[48:51]
	v_mfma_f32_16x16x32_bf16 v[36:39], v[180:183], v[204:207], v[36:39]
	v_mfma_f32_16x16x32_bf16 v[32:35], v[188:191], v[204:207], v[32:35]
	v_mfma_f32_16x16x32_bf16 v[20:23], v[180:183], v[212:215], v[20:23]
	v_mfma_f32_16x16x32_bf16 v[16:19], v[188:191], v[212:215], v[16:19]
	v_mfma_f32_16x16x32_bf16 v[4:7], v[180:183], v[220:223], v[4:7]
	v_mfma_f32_16x16x32_bf16 v[0:3], v[188:191], v[220:223], v[0:3]
	s_barrier
	s_add_i32 s51, 0, 0x18000
	v_add_u32_e32 v153, s51, v149
	s_add_i32 s52, 0, 0x1c000
	ds_read_b128 v[138:141], v153
	ds_read_b128 v[142:145], v153 offset:1024
	ds_read_b128 v[168:171], v153 offset:2048
	ds_read_b128 v[172:175], v153 offset:3072
	v_add_u32_e32 v153, s52, v149
	ds_read_b128 v[176:179], v153
	ds_read_b128 v[180:183], v153 offset:1024
	ds_read_b128 v[184:187], v153 offset:2048
	ds_read_b128 v[188:191], v153 offset:3072
	v_lshl_add_u64 v[224:225], s[14:15], 0, v[132:133]
	v_lshl_add_u64 v[226:227], s[14:15], 0, v[130:131]
	s_add_u32 s14, s14, 0x40000
	s_addc_u32 s15, s15, 0
	s_mov_b32 m0, s25
	v_lshl_add_u64 v[228:229], s[14:15], 0, v[132:133]
	ds_read_b128 v[192:195], v152 offset:32768
	ds_read_b128 v[196:199], v152 offset:33792
	ds_read_b128 v[200:203], v152 offset:34816
	ds_read_b128 v[204:207], v152 offset:35840
	ds_read_b128 v[208:211], v152 offset:36864
	ds_read_b128 v[212:215], v152 offset:37888
	ds_read_b128 v[216:219], v152 offset:38912
	ds_read_b128 v[220:223], v152 offset:39936
	global_load_lds_dwordx4 v[224:225], off
	s_mov_b32 m0, s26
	s_nop 0
	global_load_lds_dwordx4 v[226:227], off
	s_mov_b32 m0, s27
	s_nop 0
	global_load_lds_dwordx4 v[228:229], off
	v_lshl_add_u64 v[228:229], s[14:15], 0, v[130:131]
	s_mov_b32 m0, s28
	s_nop 0
	global_load_lds_dwordx4 v[228:229], off
	s_waitcnt vmcnt(8)
	s_waitcnt lgkmcnt(0)
	s_barrier
; #define PG8_STAGE(bufoff, gbase, voff) do { _Pragma("unroll") for (int _i = 0; _i < 2; ++_i) \
;         __builtin_amdgcn_global_load_lds((const unsigned*)((const char*)(gbase) + (voff)[_i]), (PG8_LAS unsigned*)(lds + (bufoff) + ldsw + _i * 8192), 16, 0, 0); } while (0)
; #define PG8_LDA(dst, b, h) do { _Pragma("unroll") for (int m = 0; m < 4; ++m) _Pragma("unroll") for (int k = 0; k < 2; ++k) dst[m][k] = *(const PG8_LAS bf16x8*)(lds + PG8_SA(b, h) + aoff + m * 2048 + k * 1024); } while (0)
; #define PG8_LDB(dst, b, h) do { _Pragma("unroll") for (int n = 0; n < 2; ++n) _Pragma("unroll") for (int k = 0; k < 2; ++k) dst[n][k] = *(const PG8_LAS bf16x8*)(lds + PG8_SB(b, h) + boff + n * 2048 + k * 1024); } while (0)
; #define PG8_MMA(ai, bj, At, Bt) do { __builtin_amdgcn_s_setprio(1); _Pragma("unroll") for (int m = 0; m < 4; ++m) _Pragma("unroll") for (int n = 0; n < 2; ++n) _Pragma("unroll") for (int k = 0; k < 2; ++k) \
;         acc[ai][bj][m][n] = __builtin_amdgcn_mfma_f32_16x16x32_bf16(Bt[n][k], At[m][k], acc[ai][bj][m][n], 0, 0, 0); __builtin_amdgcn_s_setprio(0); } while (0)
; #define PG8_WAIT_V(n) asm volatile("s_waitcnt vmcnt(" #n ")" ::: "memory")
; #define PG8_WAIT_L(n) asm volatile("s_waitcnt lgkmcnt(" #n ")" ::: "memory")
; #define PG8_BAR __builtin_amdgcn_s_barrier()
; #define PG8_SCHED __builtin_amdgcn_sched_barrier(0)
; template <class Epi, class Sched, bool ALIGN_EPI = false, bool SP2 = false>
; __device__ __forceinline__ void gemm_phase(PG8_LAS unsigned char* lds, const Gemm g, const Sched& S, const Epi& E) {
;     ...
;         for (int t = 0; t < nt; t += 2) {
;     ...
;             PG8_LDB(B0, 1, 0); PG8_LDB(B1, 1, 1); PG8_SCHED; PG8_LDA(At, 1, 0); PG8_STAGE(PG8_SA(0, 1), a2 + hstep, voffA);
;             PG8_WAIT_V(8); PG8_WAIT_L(0); PG8_BAR; PG8_MMA(0, 0, At, B0); PG8_MMA(0, 1, At, B1); PG8_BAR; PG8_SCHED;
;             PG8_LDA(At, 1, 1); PG8_STAGE(PG8_SB(1, 0), b3, voffB); PG8_STAGE(PG8_SB(1, 1), b3 + hstep, voffB); PG8_STAGE(PG8_SA(1, 0), a3, voffA);
;             PG8_WAIT_V(8); PG8_WAIT_L(0); PG8_BAR; PG8_MMA(1, 0, At, B0); PG8_MMA(1, 1, At, B1); PG8_BAR; PG8_SCHED;
	s_waitcnt lgkmcnt(0)
	v_mfma_f32_16x16x32_bf16 v[124:127], v[138:141], v[192:195], v[124:127]
	v_mfma_f32_16x16x32_bf16 v[120:123], v[168:171], v[192:195], v[120:123]
	v_mfma_f32_16x16x32_bf16 v[108:111], v[138:141], v[200:203], v[108:111]
	v_mfma_f32_16x16x32_bf16 v[104:107], v[168:171], v[200:203], v[104:107]
	v_mfma_f32_16x16x32_bf16 v[92:95], v[138:141], v[208:211], v[92:95]
	v_mfma_f32_16x16x32_bf16 v[88:91], v[168:171], v[208:211], v[88:91]
	v_mfma_f32_16x16x32_bf16 v[76:79], v[138:141], v[216:219], v[76:79]
	v_mfma_f32_16x16x32_bf16 v[72:75], v[168:171], v[216:219], v[72:75]
	v_mfma_f32_16x16x32_bf16 v[124:127], v[142:145], v[196:199], v[124:127]
	v_mfma_f32_16x16x32_bf16 v[120:123], v[172:175], v[196:199], v[120:123]
	v_mfma_f32_16x16x32_bf16 v[108:111], v[142:145], v[204:207], v[108:111]
	v_mfma_f32_16x16x32_bf16 v[104:107], v[172:175], v[204:207], v[104:107]
	v_mfma_f32_16x16x32_bf16 v[92:95], v[142:145], v[212:215], v[92:95]
	v_mfma_f32_16x16x32_bf16 v[88:91], v[172:175], v[212:215], v[88:91]
	v_mfma_f32_16x16x32_bf16 v[76:79], v[142:145], v[220:223], v[76:79]
	v_mfma_f32_16x16x32_bf16 v[72:75], v[172:175], v[220:223], v[72:75]
	v_mfma_f32_16x16x32_bf16 v[116:119], v[176:179], v[192:195], v[116:119]
	v_mfma_f32_16x16x32_bf16 v[112:115], v[184:187], v[192:195], v[112:115]
	v_mfma_f32_16x16x32_bf16 v[100:103], v[176:179], v[200:203], v[100:103]
	v_mfma_f32_16x16x32_bf16 v[96:99], v[184:187], v[200:203], v[96:99]
	v_mfma_f32_16x16x32_bf16 v[84:87], v[176:179], v[208:211], v[84:87]
	v_mfma_f32_16x16x32_bf16 v[80:83], v[184:187], v[208:211], v[80:83]
	v_mfma_f32_16x16x32_bf16 v[68:71], v[176:179], v[216:219], v[68:71]
	v_mfma_f32_16x16x32_bf16 v[64:67], v[184:187], v[216:219], v[64:67]
	v_mfma_f32_16x16x32_bf16 v[116:119], v[180:183], v[196:199], v[116:119]
	v_mfma_f32_16x16x32_bf16 v[112:115], v[188:191], v[196:199], v[112:115]
	v_mfma_f32_16x16x32_bf16 v[100:103], v[180:183], v[204:207], v[100:103]
	v_mfma_f32_16x16x32_bf16 v[96:99], v[188:191], v[204:207], v[96:99]
	v_mfma_f32_16x16x32_bf16 v[84:87], v[180:183], v[212:215], v[84:87]
	v_mfma_f32_16x16x32_bf16 v[80:83], v[188:191], v[212:215], v[80:83]
	v_mfma_f32_16x16x32_bf16 v[68:71], v[180:183], v[220:223], v[68:71]
	v_mfma_f32_16x16x32_bf16 v[64:67], v[188:191], v[220:223], v[64:67]
	s_barrier
	s_add_i32 s14, s51, s21
	v_lshl_add_u64 v[146:147], v[146:147], 0, s[96:97]
	s_mov_b32 m0, s14
	ds_read_b128 v[192:195], v152 offset:49152
	ds_read_b128 v[196:199], v152 offset:50176
	ds_read_b128 v[200:203], v152 offset:51200
	ds_read_b128 v[204:207], v152 offset:52224
	ds_read_b128 v[208:211], v152 offset:53248
	ds_read_b128 v[212:215], v152 offset:54272
	ds_read_b128 v[216:219], v152 offset:55296
	ds_read_b128 v[220:223], v152 offset:56320
	global_load_lds_dwordx4 v[146:147], off
	s_add_i32 m0, s14, 0x2000
	s_add_u32 s12, s12, 0x40080
	v_lshl_add_u64 v[146:147], v[154:155], 0, s[96:97]
	s_addc_u32 s13, s13, 0
	s_add_i32 s14, s52, s21
	global_load_lds_dwordx4 v[146:147], off
	v_lshl_add_u64 v[146:147], s[12:13], 0, v[156:157]
	s_mov_b32 m0, s14
	s_nop 0
	global_load_lds_dwordx4 v[146:147], off
	v_lshl_add_u64 v[146:147], s[12:13], 0, v[128:129]
	s_add_i32 m0, s14, 0x2000
	s_nop 0
	global_load_lds_dwordx4 v[146:147], off
	s_waitcnt vmcnt(6)
	s_waitcnt lgkmcnt(0)
	s_barrier
	s_waitcnt lgkmcnt(0)
	v_mfma_f32_16x16x32_bf16 v[60:63], v[138:141], v[192:195], v[60:63]
	v_mfma_f32_16x16x32_bf16 v[56:59], v[168:171], v[192:195], v[56:59]
	v_mfma_f32_16x16x32_bf16 v[44:47], v[138:141], v[200:203], v[44:47]
	v_mfma_f32_16x16x32_bf16 v[40:43], v[168:171], v[200:203], v[40:43]
	v_mfma_f32_16x16x32_bf16 v[28:31], v[138:141], v[208:211], v[28:31]
	v_mfma_f32_16x16x32_bf16 v[24:27], v[168:171], v[208:211], v[24:27]
	v_mfma_f32_16x16x32_bf16 v[12:15], v[138:141], v[216:219], v[12:15]
	v_mfma_f32_16x16x32_bf16 v[8:11], v[168:171], v[216:219], v[8:11]
	v_mfma_f32_16x16x32_bf16 v[60:63], v[142:145], v[196:199], v[60:63]
	v_mfma_f32_16x16x32_bf16 v[56:59], v[172:175], v[196:199], v[56:59]
	v_mfma_f32_16x16x32_bf16 v[44:47], v[142:145], v[204:207], v[44:47]
	v_mfma_f32_16x16x32_bf16 v[40:43], v[172:175], v[204:207], v[40:43]
	v_mfma_f32_16x16x32_bf16 v[28:31], v[142:145], v[212:215], v[28:31]
	v_mfma_f32_16x16x32_bf16 v[24:27], v[172:175], v[212:215], v[24:27]
	v_mfma_f32_16x16x32_bf16 v[12:15], v[142:145], v[220:223], v[12:15]
	v_mfma_f32_16x16x32_bf16 v[8:11], v[172:175], v[220:223], v[8:11]
	v_mfma_f32_16x16x32_bf16 v[52:55], v[176:179], v[192:195], v[52:55]
	v_mfma_f32_16x16x32_bf16 v[48:51], v[184:187], v[192:195], v[48:51]
	v_mfma_f32_16x16x32_bf16 v[36:39], v[176:179], v[200:203], v[36:39]
	v_mfma_f32_16x16x32_bf16 v[32:35], v[184:187], v[200:203], v[32:35]
	v_mfma_f32_16x16x32_bf16 v[20:23], v[176:179], v[208:211], v[20:23]
	v_mfma_f32_16x16x32_bf16 v[16:19], v[184:187], v[208:211], v[16:19]
	v_mfma_f32_16x16x32_bf16 v[4:7], v[176:179], v[216:219], v[4:7]
	v_mfma_f32_16x16x32_bf16 v[0:3], v[184:187], v[216:219], v[0:3]
	v_mfma_f32_16x16x32_bf16 v[52:55], v[180:183], v[196:199], v[52:55]
	v_mfma_f32_16x16x32_bf16 v[48:51], v[188:191], v[196:199], v[48:51]
	v_mfma_f32_16x16x32_bf16 v[36:39], v[180:183], v[204:207], v[36:39]
	v_mfma_f32_16x16x32_bf16 v[32:35], v[188:191], v[204:207], v[32:35]
	v_mfma_f32_16x16x32_bf16 v[20:23], v[180:183], v[212:215], v[20:23]
	v_mfma_f32_16x16x32_bf16 v[16:19], v[188:191], v[212:215], v[16:19]
	v_mfma_f32_16x16x32_bf16 v[4:7], v[180:183], v[220:223], v[4:7]
	v_mfma_f32_16x16x32_bf16 v[0:3], v[188:191], v[220:223], v[0:3]
	s_barrier
	s_add_i32 s50, s50, 2
	s_add_u32 s10, s10, 0x100
	s_addc_u32 s11, s11, 0
	s_add_u32 s48, s48, 0x100
	s_addc_u32 s49, s49, 0
	s_cmp_gt_u32 s50, 13
	s_cbranch_scc0 .LBB0_399
	s_and_b64 vcc, exec, s[6:7]
	s_cbranch_vccz .LBB0_402
	s_barrier
